# in-projection-tail layer-1 weight transposes as one batch of 6 tiles with all 24 tile loads issued up front (was 2 batches of 3); far branches of the layer loop bounced through a trampoline
# baseline (speedup 1.0000x reference)
.LBB0_178:
	s_mov_b64 s[4:5], 0
	s_mov_b32 s50, 1
	v_writelane_b32 v205, s4, 9
	s_and_b64 vcc, exec, s[2:3]
	s_movk_i32 s42, 0x4000
	v_writelane_b32 v205, s5, 10
	s_cbranch_vccz .LBB0_179
	s_endpgm

.LBB0_294:
	s_setprio 0
	s_cmp_lg_u32 s50, 0
	s_cbranch_scc1 .Lpi_skip
	s_lshr_b32 s5, s96, 3
	s_cmpk_lt_u32 s5, 43
	s_cbranch_scc1 .Lpi_skip
	s_sub_i32 s5, s5, 43
	s_lshl_b32 s5, s5, 3
	s_and_b32 s0, s96, 7
	s_or_b32 s5, s5, s0
	v_readlane_b32 s24, v207, 18
	v_readlane_b32 s25, v207, 19
	v_readlane_b32 s26, v207, 34
	v_readlane_b32 s27, v207, 35
	s_add_u32 s28, s94, 0xd00000
	s_addc_u32 s29, s95, 0
	s_add_u32 s30, s94, 0x200000
	s_addc_u32 s31, s95, 0
	v_lshrrev_b32_e32 v22, 4, v138
	v_and_b32_e32 v0, 15, v138
	v_lshlrev_b32_e32 v0, 4, v0
	v_and_b32_e32 v2, 3, v138
	v_lshlrev_b32_e32 v24, 4, v2
	v_lshlrev_b32_e32 v2, 5, v2
	v_lshrrev_b32_e32 v23, 2, v138
	v_mul_u32_u24_e32 v24, 0x41, v24
	v_and_b32_e32 v25, -4, v138
	v_lshl_add_u32 v24, v24, 2, v25
	v_mul_u32_u24_e32 v25, 0x104, v22
	v_add_u32_e32 v25, v25, v0
	v_add_u32_e32 v26, 0x1040, v25
	v_add_u32_e32 v27, 0x1048, v25
	v_add_u32_e32 v28, 0x2080, v25
	v_add_u32_e32 v29, 0x2088, v25
	v_add_u32_e32 v30, 0x30c0, v25
	v_add_u32_e32 v31, 0x30c8, v25
	v_add_u32_e32 v83, 0x400, v24
	v_add_u32_e32 v84, 0x800, v24
	v_add_u32_e32 v85, 0xc00, v24
	v_lshl_add_u32 v82, v23, 11, v2
	s_mov_b32 s1, s5
	s_movk_i32 s86, 0x3c0
	s_cmpk_lt_u32 s1, 0x2c0
	s_cselect_b32 s86, 0x2c0, s86
	s_add_i32 s1, s1, s86
	s_cmpk_gt_i32 s1, 0x57f
	s_cbranch_scc1 .Lpi_out0
	s_mul_hi_i32 s86, s1, 0x2e8ba2e9
	s_ashr_i32 s86, s86, 7
	s_mul_i32 s87, s86, 0x2c0
	s_sub_i32 s87, s1, s87
	s_mul_i32 s88, s87, 0xba3
	s_lshr_b32 s88, s88, 17
	s_mul_i32 s89, s88, 44
	s_sub_i32 s87, s87, s89
	s_mul_i32 s89, s86, 0xb00000
	s_mul_i32 s90, s88, 0xb0000
	s_add_u32 s89, s89, s90
	s_lshl_b32 s90, s87, 8
	s_add_u32 s89, s89, s90
	s_add_u32 s76, s24, s89
	s_addc_u32 s77, s25, 0
	s_sub_i32 s90, s87, 20
	s_cmp_gt_u32 s90, 15
	s_cbranch_scc1 .Lpi_nr0
	s_and_b32 s91, s87, 3
	s_lshr_b32 s90, s90, 2
	s_lshl_b32 s90, s90, 3
	s_lshr_b32 s90, 0x1d15141c, s90
	s_and_b32 s90, s90, 0xff
	s_lshl_b32 s91, s91, 1
	s_add_i32 s87, s90, s91

.Lpi_dec1:
	v_mad_u32_u24 v73, v22, s81, v0
	s_lshl_b32 s0, s81, 4
	global_load_dwordx4 v[208:211], v73, s[82:83] nt
	s_add_u32 s82, s82, s0
	s_addc_u32 s83, s83, 0
	global_load_dwordx4 v[212:215], v73, s[82:83] nt
	s_add_u32 s82, s82, s0
	s_addc_u32 s83, s83, 0
	global_load_dwordx4 v[216:219], v73, s[82:83] nt
	s_add_u32 s82, s82, s0
	s_addc_u32 s83, s83, 0
	global_load_dwordx4 v[220:223], v73, s[82:83] nt
	s_add_i32 s1, s5, 0x150
	s_movk_i32 s86, 0x3c0
	s_cmpk_lt_u32 s1, 0x2c0
	s_cselect_b32 s86, 0x2c0, s86
	s_add_i32 s1, s1, s86
	s_cmpk_gt_i32 s1, 0x57f
	s_cbranch_scc1 .Lpi_out2
	s_mul_hi_i32 s86, s1, 0x2e8ba2e9
	s_ashr_i32 s86, s86, 7
	s_mul_i32 s87, s86, 0x2c0
	s_sub_i32 s87, s1, s87
	s_mul_i32 s88, s87, 0xba3
	s_lshr_b32 s88, s88, 17
	s_mul_i32 s89, s88, 44
	s_sub_i32 s87, s87, s89
	s_mul_i32 s89, s86, 0xb00000
	s_mul_i32 s90, s88, 0xb0000
	s_add_u32 s89, s89, s90
	s_lshl_b32 s90, s87, 8
	s_add_u32 s89, s89, s90
	s_add_u32 s20, s24, s89
	s_addc_u32 s21, s25, 0
	s_sub_i32 s90, s87, 20
	s_cmp_gt_u32 s90, 15
	s_cbranch_scc1 .Lpi_nr2
	s_and_b32 s91, s87, 3
	s_lshr_b32 s90, s90, 2
	s_lshl_b32 s90, s90, 3
	s_lshr_b32 s90, 0x1d15141c, s90
	s_and_b32 s90, s90, 0xff
	s_lshl_b32 s91, s91, 1
	s_add_i32 s87, s90, s91

.Lpi_dec2:
	v_mad_u32_u24 v78, v22, s16, v0
	s_lshl_b32 s0, s16, 4
	global_load_dwordx4 v[224:227], v78, s[20:21] nt
	s_add_u32 s20, s20, s0
	s_addc_u32 s21, s21, 0
	global_load_dwordx4 v[228:231], v78, s[20:21] nt
	s_add_u32 s20, s20, s0
	s_addc_u32 s21, s21, 0
	global_load_dwordx4 v[232:235], v78, s[20:21] nt
	s_add_u32 s20, s20, s0
	s_addc_u32 s21, s21, 0
	global_load_dwordx4 v[236:239], v78, s[20:21] nt
	s_add_i32 s1, s5, 0x1f8
	s_movk_i32 s86, 0x3c0
	s_cmpk_lt_u32 s1, 0x2c0
	s_cselect_b32 s86, 0x2c0, s86
	s_add_i32 s1, s1, s86
	s_cmpk_gt_i32 s1, 0x57f
	s_cbranch_scc1 .Lpi_out3
	s_mul_hi_i32 s86, s1, 0x2e8ba2e9
	s_ashr_i32 s86, s86, 7
	s_mul_i32 s87, s86, 0x2c0
	s_sub_i32 s87, s1, s87
	s_mul_i32 s88, s87, 0xba3
	s_lshr_b32 s88, s88, 17
	s_mul_i32 s89, s88, 44
	s_sub_i32 s87, s87, s89
	s_mul_i32 s89, s86, 0xb00000
	s_mul_i32 s90, s88, 0xb0000
	s_add_u32 s89, s89, s90
	s_lshl_b32 s90, s87, 8
	s_add_u32 s89, s89, s90
	s_add_u32 s56, s24, s89
	s_addc_u32 s57, s25, 0
	s_sub_i32 s90, s87, 20
	s_cmp_gt_u32 s90, 15
	s_cbranch_scc1 .Lpi_nr3
	s_and_b32 s91, s87, 3
	s_lshr_b32 s90, s90, 2
	s_lshl_b32 s90, s90, 3
	s_lshr_b32 s90, 0x1d15141c, s90
	s_and_b32 s90, s90, 0xff
	s_lshl_b32 s91, s91, 1
	s_add_i32 s87, s90, s91
.Lpi_nr3:
	s_mul_i32 s89, s86, 0x580000
	s_lshl_b32 s90, s87, 17
	s_add_u32 s89, s89, s90
	s_lshl_b32 s90, s88, 7
	s_add_u32 s89, s89, s90
	s_add_u32 s58, s30, s89
	s_addc_u32 s59, s31, 0
	s_movk_i32 s17, 0x2c00
	s_branch .Lpi_dec3
.Lpi_out3:
	s_add_i32 s87, s1, 0xfffffa80
	s_lshr_b32 s86, s87, 8
	s_bfe_u32 s88, s87, 0x40004
	s_and_b32 s87, s87, 15
	s_lshl_b32 s89, s86, 22
	s_lshl_b32 s90, s88, 18
	s_add_u32 s89, s89, s90
	s_lshl_b32 s90, s87, 8
	s_add_u32 s89, s89, s90
	s_add_u32 s56, s26, s89
	s_addc_u32 s57, s27, 0
	s_lshl_b32 s89, s86, 21
	s_lshl_b32 s90, s87, 17
	s_add_u32 s89, s89, s90
	s_lshl_b32 s90, s88, 7
	s_add_u32 s89, s89, s90
	s_add_u32 s58, s28, s89
	s_addc_u32 s59, s29, 0
	s_movk_i32 s17, 0x1000
.Lpi_dec3:
	v_mad_u32_u24 v80, v22, s17, v0
	s_lshl_b32 s0, s17, 4
	global_load_dwordx4 v[240:243], v80, s[56:57] nt
	s_add_u32 s56, s56, s0
	s_addc_u32 s57, s57, 0
	global_load_dwordx4 v[244:247], v80, s[56:57] nt
	s_add_u32 s56, s56, s0
	s_addc_u32 s57, s57, 0
	global_load_dwordx4 v[64:67], v80, s[56:57] nt
	s_add_u32 s56, s56, s0
	s_addc_u32 s57, s57, 0
	global_load_dwordx4 v[68:71], v80, s[56:57] nt
	s_add_i32 s1, s5, 0x2a0
	s_movk_i32 s86, 0x3c0
	s_cmpk_lt_u32 s1, 0x2c0
	s_cselect_b32 s86, 0x2c0, s86
	s_add_i32 s1, s1, s86
	s_cmpk_gt_i32 s1, 0x57f
	s_cbranch_scc1 .Lpi_out4
	s_mul_hi_i32 s86, s1, 0x2e8ba2e9
	s_ashr_i32 s86, s86, 7
	s_mul_i32 s87, s86, 0x2c0
	s_sub_i32 s87, s1, s87
	s_mul_i32 s88, s87, 0xba3
	s_lshr_b32 s88, s88, 17
	s_mul_i32 s89, s88, 44
	s_sub_i32 s87, s87, s89
	s_mul_i32 s89, s86, 0xb00000
	s_mul_i32 s90, s88, 0xb0000
	s_add_u32 s89, s89, s90
	s_lshl_b32 s90, s87, 8
	s_add_u32 s89, s89, s90
	s_add_u32 s60, s24, s89
	s_addc_u32 s61, s25, 0
	s_sub_i32 s90, s87, 20
	s_cmp_gt_u32 s90, 15
	s_cbranch_scc1 .Lpi_nr4
	s_and_b32 s91, s87, 3
	s_lshr_b32 s90, s90, 2
	s_lshl_b32 s90, s90, 3
	s_lshr_b32 s90, 0x1d15141c, s90
	s_and_b32 s90, s90, 0xff
	s_lshl_b32 s91, s91, 1
	s_add_i32 s87, s90, s91
.Lpi_nr4:
	s_mul_i32 s89, s86, 0x580000
	s_lshl_b32 s90, s87, 17
	s_add_u32 s89, s89, s90
	s_lshl_b32 s90, s88, 7
	s_add_u32 s89, s89, s90
	s_add_u32 s62, s30, s89
	s_addc_u32 s63, s31, 0
	s_movk_i32 s18, 0x2c00
	s_branch .Lpi_dec4
.Lpi_out4:
	s_add_i32 s87, s1, 0xfffffa80
	s_lshr_b32 s86, s87, 8
	s_bfe_u32 s88, s87, 0x40004
	s_and_b32 s87, s87, 15
	s_lshl_b32 s89, s86, 22
	s_lshl_b32 s90, s88, 18
	s_add_u32 s89, s89, s90
	s_lshl_b32 s90, s87, 8
	s_add_u32 s89, s89, s90
	s_add_u32 s60, s26, s89
	s_addc_u32 s61, s27, 0
	s_lshl_b32 s89, s86, 21
	s_lshl_b32 s90, s87, 17
	s_add_u32 s89, s89, s90
	s_lshl_b32 s90, s88, 7
	s_add_u32 s89, s89, s90
	s_add_u32 s62, s28, s89
	s_addc_u32 s63, s29, 0
	s_movk_i32 s18, 0x1000
.Lpi_dec4:
	v_mad_u32_u24 v94, v22, s18, v0
	s_lshl_b32 s0, s18, 4
	global_load_dwordx4 v[86:89], v94, s[60:61] nt
	s_add_u32 s60, s60, s0
	s_addc_u32 s61, s61, 0
	global_load_dwordx4 v[90:93], v94, s[60:61] nt
	s_add_u32 s60, s60, s0
	s_addc_u32 s61, s61, 0
	global_load_dwordx4 v[116:119], v94, s[60:61] nt
	s_add_u32 s60, s60, s0
	s_addc_u32 s61, s61, 0
	global_load_dwordx4 v[120:123], v94, s[60:61] nt
	s_add_i32 s1, s5, 0x348
	s_cmpk_gt_u32 s1, 0x3bf
	s_cbranch_scc1 .Lpi_dummy
	s_movk_i32 s86, 0x3c0
	s_cmpk_lt_u32 s1, 0x2c0
	s_cselect_b32 s86, 0x2c0, s86
	s_add_i32 s1, s1, s86
	s_cmpk_gt_i32 s1, 0x57f
	s_cbranch_scc1 .Lpi_out5
	s_mul_hi_i32 s86, s1, 0x2e8ba2e9
	s_ashr_i32 s86, s86, 7
	s_mul_i32 s87, s86, 0x2c0
	s_sub_i32 s87, s1, s87
	s_mul_i32 s88, s87, 0xba3
	s_lshr_b32 s88, s88, 17
	s_mul_i32 s89, s88, 44
	s_sub_i32 s87, s87, s89
	s_mul_i32 s89, s86, 0xb00000
	s_mul_i32 s90, s88, 0xb0000
	s_add_u32 s89, s89, s90
	s_lshl_b32 s90, s87, 8
	s_add_u32 s89, s89, s90
	s_add_u32 s48, s24, s89
	s_addc_u32 s49, s25, 0
	s_sub_i32 s90, s87, 20
	s_cmp_gt_u32 s90, 15
	s_cbranch_scc1 .Lpi_nr5
	s_and_b32 s91, s87, 3
	s_lshr_b32 s90, s90, 2
	s_lshl_b32 s90, s90, 3
	s_lshr_b32 s90, 0x1d15141c, s90
	s_and_b32 s90, s90, 0xff
	s_lshl_b32 s91, s91, 1
	s_add_i32 s87, s90, s91
.Lpi_nr5:
	s_mul_i32 s89, s86, 0x580000
	s_lshl_b32 s90, s87, 17
	s_add_u32 s89, s89, s90
	s_lshl_b32 s90, s88, 7
	s_add_u32 s89, s89, s90
	s_add_u32 s8, s30, s89
	s_addc_u32 s9, s31, 0
	s_movk_i32 s40, 0x2c00
	s_branch .Lpi_dec5
.Lpi_out5:
	s_add_i32 s87, s1, 0xfffffa80
	s_lshr_b32 s86, s87, 8
	s_bfe_u32 s88, s87, 0x40004
	s_and_b32 s87, s87, 15
	s_lshl_b32 s89, s86, 22
	s_lshl_b32 s90, s88, 18
	s_add_u32 s89, s89, s90
	s_lshl_b32 s90, s87, 8
	s_add_u32 s89, s89, s90
	s_add_u32 s48, s26, s89
	s_addc_u32 s49, s27, 0
	s_lshl_b32 s89, s86, 21
	s_lshl_b32 s90, s87, 17
	s_add_u32 s89, s89, s90
	s_lshl_b32 s90, s88, 7
	s_add_u32 s89, s89, s90
	s_add_u32 s8, s28, s89
	s_addc_u32 s9, s29, 0
	s_movk_i32 s40, 0x1000
	s_branch .Lpi_dec5
.Lpi_dummy:
	s_mov_b32 s48, s24
	s_mov_b32 s49, s25
	s_movk_i32 s40, 0x2c00
	s_mov_b32 s3, 0
	s_branch .Lpi_ldl

.Lpi_ldl:
	v_mad_u32_u24 v95, v22, s40, v0
	s_lshl_b32 s0, s40, 4
	global_load_dwordx4 v[98:101], v95, s[48:49] nt
	s_add_u32 s48, s48, s0
	s_addc_u32 s49, s49, 0
	global_load_dwordx4 v[104:107], v95, s[48:49] nt
	s_add_u32 s48, s48, s0
	s_addc_u32 s49, s49, 0
	global_load_dwordx4 v[110:113], v95, s[48:49] nt
	s_add_u32 s48, s48, s0
	s_addc_u32 s49, s49, 0
	global_load_dwordx4 v[200:203], v95, s[48:49] nt
	s_barrier
	s_waitcnt vmcnt(23)
	ds_write2_b32 v25, v4, v5 offset1:1
	ds_write2_b32 v25, v6, v7 offset0:2 offset1:3
	s_waitcnt vmcnt(22)
	ds_write2_b32 v26, v8, v9 offset1:1
	ds_write2_b32 v27, v10, v11 offset1:1
	s_waitcnt vmcnt(21)
	ds_write2_b32 v28, v12, v13 offset1:1
	ds_write2_b32 v29, v14, v15 offset1:1
	s_waitcnt vmcnt(20)
	ds_write2_b32 v30, v16, v17 offset1:1
	ds_write2_b32 v31, v18, v19 offset1:1
	s_waitcnt lgkmcnt(0)
	s_barrier
	ds_read2_b32 v[4:5], v24 offset1:65
	ds_read2_b32 v[6:7], v24 offset0:130 offset1:195
	ds_read2_b32 v[8:9], v83 offset0:4 offset1:69
	ds_read2_b32 v[10:11], v83 offset0:134 offset1:199
	ds_read2_b32 v[12:13], v84 offset0:8 offset1:73
	ds_read2_b32 v[14:15], v84 offset0:138 offset1:203
	ds_read2_b32 v[16:17], v85 offset0:12 offset1:77
	ds_read2_b32 v[18:19], v85 offset0:142 offset1:207
	s_waitcnt lgkmcnt(7)
	v_cvt_pk_bf16_f32 v4, v4, v5
	s_waitcnt lgkmcnt(6)
	v_cvt_pk_bf16_f32 v5, v6, v7
	s_waitcnt lgkmcnt(5)
	v_cvt_pk_bf16_f32 v6, v8, v9
	s_waitcnt lgkmcnt(4)
	v_cvt_pk_bf16_f32 v7, v10, v11
	s_waitcnt lgkmcnt(3)
	v_cvt_pk_bf16_f32 v8, v12, v13
	s_waitcnt lgkmcnt(2)
	v_cvt_pk_bf16_f32 v9, v14, v15
	s_waitcnt lgkmcnt(1)
	v_cvt_pk_bf16_f32 v10, v16, v17
	s_waitcnt lgkmcnt(0)
	v_cvt_pk_bf16_f32 v11, v18, v19
	global_store_dwordx4 v82, v[4:7], s[78:79]
	global_store_dwordx4 v82, v[8:11], s[78:79] offset:16
	s_barrier
	s_waitcnt vmcnt(21)
	ds_write2_b32 v25, v208, v209 offset1:1
	ds_write2_b32 v25, v210, v211 offset0:2 offset1:3
	s_waitcnt vmcnt(20)
	ds_write2_b32 v26, v212, v213 offset1:1
	ds_write2_b32 v27, v214, v215 offset1:1
	s_waitcnt vmcnt(19)
	ds_write2_b32 v28, v216, v217 offset1:1
	ds_write2_b32 v29, v218, v219 offset1:1
	s_waitcnt vmcnt(18)
	ds_write2_b32 v30, v220, v221 offset1:1
	ds_write2_b32 v31, v222, v223 offset1:1
	s_waitcnt lgkmcnt(0)
	s_barrier
	ds_read2_b32 v[4:5], v24 offset1:65
	ds_read2_b32 v[6:7], v24 offset0:130 offset1:195
	ds_read2_b32 v[8:9], v83 offset0:4 offset1:69
	ds_read2_b32 v[10:11], v83 offset0:134 offset1:199
	ds_read2_b32 v[12:13], v84 offset0:8 offset1:73
	ds_read2_b32 v[14:15], v84 offset0:138 offset1:203
	ds_read2_b32 v[16:17], v85 offset0:12 offset1:77
	ds_read2_b32 v[18:19], v85 offset0:142 offset1:207
	s_waitcnt lgkmcnt(7)
	v_cvt_pk_bf16_f32 v4, v4, v5
	s_waitcnt lgkmcnt(6)
	v_cvt_pk_bf16_f32 v5, v6, v7
	s_waitcnt lgkmcnt(5)
	v_cvt_pk_bf16_f32 v6, v8, v9
	s_waitcnt lgkmcnt(4)
	v_cvt_pk_bf16_f32 v7, v10, v11
	s_waitcnt lgkmcnt(3)
	v_cvt_pk_bf16_f32 v8, v12, v13
	s_waitcnt lgkmcnt(2)
	v_cvt_pk_bf16_f32 v9, v14, v15
	s_waitcnt lgkmcnt(1)
	v_cvt_pk_bf16_f32 v10, v16, v17
	s_waitcnt lgkmcnt(0)
	v_cvt_pk_bf16_f32 v11, v18, v19
	global_store_dwordx4 v82, v[4:7], s[84:85]
	global_store_dwordx4 v82, v[8:11], s[84:85] offset:16
	s_barrier
	s_waitcnt vmcnt(19)
	ds_write2_b32 v25, v224, v225 offset1:1
	ds_write2_b32 v25, v226, v227 offset0:2 offset1:3
	s_waitcnt vmcnt(18)
	ds_write2_b32 v26, v228, v229 offset1:1
	ds_write2_b32 v27, v230, v231 offset1:1
	s_waitcnt vmcnt(17)
	ds_write2_b32 v28, v232, v233 offset1:1
	ds_write2_b32 v29, v234, v235 offset1:1
	s_waitcnt vmcnt(16)
	ds_write2_b32 v30, v236, v237 offset1:1
	ds_write2_b32 v31, v238, v239 offset1:1
	s_waitcnt lgkmcnt(0)
	s_barrier
	ds_read2_b32 v[4:5], v24 offset1:65
	ds_read2_b32 v[6:7], v24 offset0:130 offset1:195
	ds_read2_b32 v[8:9], v83 offset0:4 offset1:69
	ds_read2_b32 v[10:11], v83 offset0:134 offset1:199
	ds_read2_b32 v[12:13], v84 offset0:8 offset1:73
	ds_read2_b32 v[14:15], v84 offset0:138 offset1:203
	ds_read2_b32 v[16:17], v85 offset0:12 offset1:77
	ds_read2_b32 v[18:19], v85 offset0:142 offset1:207
	s_waitcnt lgkmcnt(7)
	v_cvt_pk_bf16_f32 v4, v4, v5
	s_waitcnt lgkmcnt(6)
	v_cvt_pk_bf16_f32 v5, v6, v7
	s_waitcnt lgkmcnt(5)
	v_cvt_pk_bf16_f32 v6, v8, v9
	s_waitcnt lgkmcnt(4)
	v_cvt_pk_bf16_f32 v7, v10, v11
	s_waitcnt lgkmcnt(3)
	v_cvt_pk_bf16_f32 v8, v12, v13
	s_waitcnt lgkmcnt(2)
	v_cvt_pk_bf16_f32 v9, v14, v15
	s_waitcnt lgkmcnt(1)
	v_cvt_pk_bf16_f32 v10, v16, v17
	s_waitcnt lgkmcnt(0)
	v_cvt_pk_bf16_f32 v11, v18, v19
	global_store_dwordx4 v82, v[4:7], s[22:23]
	global_store_dwordx4 v82, v[8:11], s[22:23] offset:16
	s_barrier
	s_waitcnt vmcnt(17)
	ds_write2_b32 v25, v240, v241 offset1:1
	ds_write2_b32 v25, v242, v243 offset0:2 offset1:3
	s_waitcnt vmcnt(16)
	ds_write2_b32 v26, v244, v245 offset1:1
	ds_write2_b32 v27, v246, v247 offset1:1
	s_waitcnt vmcnt(15)
	ds_write2_b32 v28, v64, v65 offset1:1
	ds_write2_b32 v29, v66, v67 offset1:1
	s_waitcnt vmcnt(14)
	ds_write2_b32 v30, v68, v69 offset1:1
	ds_write2_b32 v31, v70, v71 offset1:1
	s_waitcnt lgkmcnt(0)
	s_barrier
	ds_read2_b32 v[4:5], v24 offset1:65
	ds_read2_b32 v[6:7], v24 offset0:130 offset1:195
	ds_read2_b32 v[8:9], v83 offset0:4 offset1:69
	ds_read2_b32 v[10:11], v83 offset0:134 offset1:199
	ds_read2_b32 v[12:13], v84 offset0:8 offset1:73
	ds_read2_b32 v[14:15], v84 offset0:138 offset1:203
	ds_read2_b32 v[16:17], v85 offset0:12 offset1:77
	ds_read2_b32 v[18:19], v85 offset0:142 offset1:207
	s_waitcnt lgkmcnt(7)
	v_cvt_pk_bf16_f32 v4, v4, v5
	s_waitcnt lgkmcnt(6)
	v_cvt_pk_bf16_f32 v5, v6, v7
	s_waitcnt lgkmcnt(5)
	v_cvt_pk_bf16_f32 v6, v8, v9
	s_waitcnt lgkmcnt(4)
	v_cvt_pk_bf16_f32 v7, v10, v11
	s_waitcnt lgkmcnt(3)
	v_cvt_pk_bf16_f32 v8, v12, v13
	s_waitcnt lgkmcnt(2)
	v_cvt_pk_bf16_f32 v9, v14, v15
	s_waitcnt lgkmcnt(1)
	v_cvt_pk_bf16_f32 v10, v16, v17
	s_waitcnt lgkmcnt(0)
	v_cvt_pk_bf16_f32 v11, v18, v19
	global_store_dwordx4 v82, v[4:7], s[58:59]
	global_store_dwordx4 v82, v[8:11], s[58:59] offset:16
	s_barrier
	s_waitcnt vmcnt(15)
	ds_write2_b32 v25, v86, v87 offset1:1
	ds_write2_b32 v25, v88, v89 offset0:2 offset1:3
	s_waitcnt vmcnt(14)
	ds_write2_b32 v26, v90, v91 offset1:1
	ds_write2_b32 v27, v92, v93 offset1:1
	s_waitcnt vmcnt(13)
	ds_write2_b32 v28, v116, v117 offset1:1
	ds_write2_b32 v29, v118, v119 offset1:1
	s_waitcnt vmcnt(12)
	ds_write2_b32 v30, v120, v121 offset1:1
	ds_write2_b32 v31, v122, v123 offset1:1
	s_waitcnt lgkmcnt(0)
	s_barrier
	ds_read2_b32 v[4:5], v24 offset1:65
	ds_read2_b32 v[6:7], v24 offset0:130 offset1:195
	ds_read2_b32 v[8:9], v83 offset0:4 offset1:69
	ds_read2_b32 v[10:11], v83 offset0:134 offset1:199
	ds_read2_b32 v[12:13], v84 offset0:8 offset1:73
	ds_read2_b32 v[14:15], v84 offset0:138 offset1:203
	ds_read2_b32 v[16:17], v85 offset0:12 offset1:77
	ds_read2_b32 v[18:19], v85 offset0:142 offset1:207
	s_waitcnt lgkmcnt(7)
	v_cvt_pk_bf16_f32 v4, v4, v5
	s_waitcnt lgkmcnt(6)
	v_cvt_pk_bf16_f32 v5, v6, v7
	s_waitcnt lgkmcnt(5)
	v_cvt_pk_bf16_f32 v6, v8, v9
	s_waitcnt lgkmcnt(4)
	v_cvt_pk_bf16_f32 v7, v10, v11
	s_waitcnt lgkmcnt(3)
	v_cvt_pk_bf16_f32 v8, v12, v13
	s_waitcnt lgkmcnt(2)
	v_cvt_pk_bf16_f32 v9, v14, v15
	s_waitcnt lgkmcnt(1)
	v_cvt_pk_bf16_f32 v10, v16, v17
	s_waitcnt lgkmcnt(0)
	v_cvt_pk_bf16_f32 v11, v18, v19
	global_store_dwordx4 v82, v[4:7], s[62:63]
	global_store_dwordx4 v82, v[8:11], s[62:63] offset:16
	s_cmp_eq_u32 s3, 0
	s_cbranch_scc1 .Lpi_done
	s_barrier
	s_waitcnt vmcnt(13)
	ds_write2_b32 v25, v98, v99 offset1:1
	ds_write2_b32 v25, v100, v101 offset0:2 offset1:3
	s_waitcnt vmcnt(12)
	ds_write2_b32 v26, v104, v105 offset1:1
	ds_write2_b32 v27, v106, v107 offset1:1
	s_waitcnt vmcnt(11)
	ds_write2_b32 v28, v110, v111 offset1:1
	ds_write2_b32 v29, v112, v113 offset1:1
	s_waitcnt vmcnt(10)
	ds_write2_b32 v30, v200, v201 offset1:1
	ds_write2_b32 v31, v202, v203 offset1:1
	s_waitcnt lgkmcnt(0)
	s_barrier
	ds_read2_b32 v[4:5], v24 offset1:65
	ds_read2_b32 v[6:7], v24 offset0:130 offset1:195
	ds_read2_b32 v[8:9], v83 offset0:4 offset1:69
	ds_read2_b32 v[10:11], v83 offset0:134 offset1:199
	ds_read2_b32 v[12:13], v84 offset0:8 offset1:73
	ds_read2_b32 v[14:15], v84 offset0:138 offset1:203
	ds_read2_b32 v[16:17], v85 offset0:12 offset1:77
	ds_read2_b32 v[18:19], v85 offset0:142 offset1:207
	s_waitcnt lgkmcnt(7)
	v_cvt_pk_bf16_f32 v4, v4, v5
	s_waitcnt lgkmcnt(6)
	v_cvt_pk_bf16_f32 v5, v6, v7
	s_waitcnt lgkmcnt(5)
	v_cvt_pk_bf16_f32 v6, v8, v9
	s_waitcnt lgkmcnt(4)
	v_cvt_pk_bf16_f32 v7, v10, v11
	s_waitcnt lgkmcnt(3)
	v_cvt_pk_bf16_f32 v8, v12, v13
	s_waitcnt lgkmcnt(2)
	v_cvt_pk_bf16_f32 v9, v14, v15
	s_waitcnt lgkmcnt(1)
	v_cvt_pk_bf16_f32 v10, v16, v17
	s_waitcnt lgkmcnt(0)
	v_cvt_pk_bf16_f32 v11, v18, v19
	global_store_dwordx4 v82, v[4:7], s[8:9]
	global_store_dwordx4 v82, v[8:11], s[8:9] offset:16
.Lpi_done:
.Lpi_skip:
	s_waitcnt vmcnt(0)
	s_barrier
	s_mov_b64 s[0:1], exec
	v_readlane_b32 s2, v207, 0
	v_readlane_b32 s3, v207, 1
	v_readlane_b32 s58, v205, 12
	s_and_b64 s[2:3], s[0:1], s[2:3]
	v_readlane_b32 s59, v205, 13
	s_movk_i32 s20, 0x4200
	v_readlane_b32 s8, v205, 18
	s_mov_b64 exec, s[2:3]
	s_cbranch_execz .LBB0_342
	s_waitcnt vmcnt(0) expcnt(0) lgkmcnt(0)
	ds_read_b32 v2, v140
	ds_read_b32 v0, v141
	s_waitcnt lgkmcnt(1)
	v_cmp_ne_u32_e32 vcc, 0, v2
	s_cbranch_vccnz .LBB0_310
	v_readlane_b32 s12, v207, 52
	v_readlane_b32 s13, v207, 53
	s_load_dwordx2 s[2:3], s[12:13], 0x4
	s_mov_b32 s36, 1
	s_waitcnt lgkmcnt(0)
	s_mul_i32 s18, s2, s8
	s_mul_i32 s18, s18, s3
	s_branch .LBB0_298

.Lat_rare7_ret:
	v_add_f32_e32 v128, v128, v134
	s_waitcnt vmcnt(0)
	s_barrier
	s_sub_u32 s82, s82, 1
	s_cmp_lg_u32 s82, 0
	s_cbranch_scc1 .Lat_loop
	s_setprio 0
	v_cvt_pk_bf16_f32 v112, v80, v81
	v_cvt_pk_bf16_f32 v113, v82, v83
	v_cvt_pk_bf16_f32 v114, v84, v85
	v_cvt_pk_bf16_f32 v115, v86, v87
	v_cvt_pk_bf16_f32 v116, v88, v89
	v_cvt_pk_bf16_f32 v117, v90, v91
	v_cvt_pk_bf16_f32 v118, v92, v93
	v_cvt_pk_bf16_f32 v119, v94, v95
	s_waitcnt lgkmcnt(0)
	v_mfma_f32_32x32x16_bf16 v[32:47], v[192:195], v[112:115], v[32:47]
	v_mfma_f32_32x32x16_bf16 v[48:63], v[196:199], v[112:115], v[48:63]
	v_mfma_f32_32x32x16_bf16 v[32:47], v[200:203], v[116:119], v[32:47]
	v_mfma_f32_32x32x16_bf16 v[48:63], v[240:243], v[116:119], v[48:63]
	s_nop 7
	s_nop 7
	s_waitcnt vmcnt(0)
	s_lshr_b32 s0, s2, 8
	s_lshl_b32 s0, s0, 13
	s_and_b32 s1, s2, 63
	s_lshl_b32 s1, s1, 7
	s_or_b32 s0, s0, s1
	s_bfe_u32 s1, s2, 0x20006
	s_lshl_b32 s1, s1, 7
	s_add_u32 s86, s94, 0x3200000
	s_addc_u32 s87, s95, 0
	s_add_u32 s88, s94, 0x1100200
	s_addc_u32 s89, s95, 0
	v_lshrrev_b32_e32 v0, 1, v138
	v_and_b32_e32 v0, 0xe0, v0
	v_and_or_b32 v0, v138, 31, v0
	v_add_u32_e32 v0, s0, v0
	v_bfe_u32 v3, v138, 5, 1
	v_lshl_add_u32 v3, v3, 3, s1
	v_mul_lo_u32 v1, v0, s64
	v_add_u32_e32 v1, v1, v3
	v_lshl_add_u32 v2, v0, 11, v3
	v_bfe_u32 v13, v138, 5, 1
	v_lshl_add_u32 v2, v13, 3, v2
	v_lshl_add_u32 v1, v13, 3, v1
	global_load_dwordx4 v[64:67], v1, s[86:87]
	global_load_dwordx4 v[68:71], v1, s[86:87] offset:32
	global_load_dwordx4 v[72:75], v1, s[86:87] offset:64
	global_load_dwordx4 v[76:79], v1, s[86:87] offset:96
	v_mbcnt_lo_u32_b32 v4, -1, 0
	v_mbcnt_hi_u32_b32 v4, -1, v4
	v_xor_b32_e32 v4, 32, v4
	v_lshlrev_b32_e32 v4, 2, v4
	ds_bpermute_b32 v5, v4, v128
	s_waitcnt lgkmcnt(0)
	v_add_f32_e32 v5, v128, v5
	v_mov_b32_e32 v7, 1.0
	v_div_scale_f32 v8, s[0:1], v5, v5, v7
	v_rcp_f32_e32 v9, v8
	s_nop 0
	v_fma_f32 v10, -v8, v9, 1.0
	v_fmac_f32_e32 v9, v10, v9
	v_div_scale_f32 v10, vcc, v7, v5, v7
	v_mul_f32_e32 v11, v10, v9
	v_fma_f32 v12, -v8, v11, v10
	v_fmac_f32_e32 v11, v12, v9
	v_fma_f32 v8, -v8, v11, v10
	v_div_fmas_f32 v8, v8, v9, v11
	v_div_fixup_f32 v6, v8, v5, v7
	s_waitcnt vmcnt(3)
	v_permlane32_swap_b32 v64, v66
	v_permlane32_swap_b32 v65, v67
	s_nop 0
	v_lshlrev_b32_e32 v16, 16, v64
	v_and_b32_e32 v17, 0xffff0000, v64
	v_lshlrev_b32_e32 v18, 16, v65
	v_and_b32_e32 v19, 0xffff0000, v65
	v_mul_f32_e32 v20, 0xbfb8aa3b, v16
	v_mul_f32_e32 v21, 0xbfb8aa3b, v17
	v_mul_f32_e32 v22, 0xbfb8aa3b, v18
	v_mul_f32_e32 v23, 0xbfb8aa3b, v19
	v_exp_f32_e32 v20, v20
	v_exp_f32_e32 v21, v21
	v_exp_f32_e32 v22, v22
	v_exp_f32_e32 v23, v23
	s_nop 0
	v_add_f32_e32 v20, 1.0, v20
	v_add_f32_e32 v21, 1.0, v21
	v_add_f32_e32 v22, 1.0, v22
	v_add_f32_e32 v23, 1.0, v23
	v_div_scale_f32 v8, s[0:1], v20, v20, v16
	v_rcp_f32_e32 v9, v8
	s_nop 0
	v_fma_f32 v10, -v8, v9, 1.0
	v_fmac_f32_e32 v9, v10, v9
	v_div_scale_f32 v10, vcc, v16, v20, v16
	v_mul_f32_e32 v11, v10, v9
	v_fma_f32 v12, -v8, v11, v10
	v_fmac_f32_e32 v11, v12, v9
	v_fma_f32 v8, -v8, v11, v10
	v_div_fmas_f32 v8, v8, v9, v11
	v_div_fixup_f32 v24, v8, v20, v16
	v_div_scale_f32 v8, s[0:1], v21, v21, v17
	v_rcp_f32_e32 v9, v8
	s_nop 0
	v_fma_f32 v10, -v8, v9, 1.0
	v_fmac_f32_e32 v9, v10, v9
	v_div_scale_f32 v10, vcc, v17, v21, v17
	v_mul_f32_e32 v11, v10, v9
	v_fma_f32 v12, -v8, v11, v10
	v_fmac_f32_e32 v11, v12, v9
	v_fma_f32 v8, -v8, v11, v10
	v_div_fmas_f32 v8, v8, v9, v11
	v_div_fixup_f32 v25, v8, v21, v17
	v_div_scale_f32 v8, s[0:1], v22, v22, v18
	v_rcp_f32_e32 v9, v8
	s_nop 0
	v_fma_f32 v10, -v8, v9, 1.0
	v_fmac_f32_e32 v9, v10, v9
	v_div_scale_f32 v10, vcc, v18, v22, v18
	v_mul_f32_e32 v11, v10, v9
	v_fma_f32 v12, -v8, v11, v10
	v_fmac_f32_e32 v11, v12, v9
	v_fma_f32 v8, -v8, v11, v10
	v_div_fmas_f32 v8, v8, v9, v11
	v_div_fixup_f32 v26, v8, v22, v18
	v_div_scale_f32 v8, s[0:1], v23, v23, v19
	v_rcp_f32_e32 v9, v8
	s_nop 0
	v_fma_f32 v10, -v8, v9, 1.0
	v_fmac_f32_e32 v9, v10, v9
	v_div_scale_f32 v10, vcc, v19, v23, v19
	v_mul_f32_e32 v11, v10, v9
	v_fma_f32 v12, -v8, v11, v10
	v_fmac_f32_e32 v11, v12, v9
	v_fma_f32 v8, -v8, v11, v10
	v_div_fmas_f32 v8, v8, v9, v11
	v_div_fixup_f32 v27, v8, v23, v19
	v_mul_f32_e32 v24, v24, v32
	v_mul_f32_e32 v25, v25, v33
	v_mul_f32_e32 v26, v26, v34
	v_mul_f32_e32 v27, v27, v35
	v_mul_f32_e32 v24, v24, v6
	v_mul_f32_e32 v25, v25, v6
	v_mul_f32_e32 v26, v26, v6
	v_mul_f32_e32 v27, v27, v6
	v_cvt_pk_bf16_f32 v28, v24, v25
	v_cvt_pk_bf16_f32 v29, v26, v27
	v_lshlrev_b32_e32 v16, 16, v66
	v_and_b32_e32 v17, 0xffff0000, v66
	v_lshlrev_b32_e32 v18, 16, v67
	v_and_b32_e32 v19, 0xffff0000, v67
	v_mul_f32_e32 v20, 0xbfb8aa3b, v16
	v_mul_f32_e32 v21, 0xbfb8aa3b, v17
	v_mul_f32_e32 v22, 0xbfb8aa3b, v18
	v_mul_f32_e32 v23, 0xbfb8aa3b, v19
	v_exp_f32_e32 v20, v20
	v_exp_f32_e32 v21, v21
	v_exp_f32_e32 v22, v22
	v_exp_f32_e32 v23, v23
	s_nop 0
	v_add_f32_e32 v20, 1.0, v20
	v_add_f32_e32 v21, 1.0, v21
	v_add_f32_e32 v22, 1.0, v22
	v_add_f32_e32 v23, 1.0, v23
	v_div_scale_f32 v8, s[0:1], v20, v20, v16
	v_rcp_f32_e32 v9, v8
	s_nop 0
	v_fma_f32 v10, -v8, v9, 1.0
	v_fmac_f32_e32 v9, v10, v9
	v_div_scale_f32 v10, vcc, v16, v20, v16
	v_mul_f32_e32 v11, v10, v9
	v_fma_f32 v12, -v8, v11, v10
	v_fmac_f32_e32 v11, v12, v9
	v_fma_f32 v8, -v8, v11, v10
	v_div_fmas_f32 v8, v8, v9, v11
	v_div_fixup_f32 v24, v8, v20, v16
	v_div_scale_f32 v8, s[0:1], v21, v21, v17
	v_rcp_f32_e32 v9, v8
	s_nop 0
	v_fma_f32 v10, -v8, v9, 1.0
	v_fmac_f32_e32 v9, v10, v9
	v_div_scale_f32 v10, vcc, v17, v21, v17
	v_mul_f32_e32 v11, v10, v9
	v_fma_f32 v12, -v8, v11, v10
	v_fmac_f32_e32 v11, v12, v9
	v_fma_f32 v8, -v8, v11, v10
	v_div_fmas_f32 v8, v8, v9, v11
	v_div_fixup_f32 v25, v8, v21, v17
	v_div_scale_f32 v8, s[0:1], v22, v22, v18
	v_rcp_f32_e32 v9, v8
	s_nop 0
	v_fma_f32 v10, -v8, v9, 1.0
	v_fmac_f32_e32 v9, v10, v9
	v_div_scale_f32 v10, vcc, v18, v22, v18
	v_mul_f32_e32 v11, v10, v9
	v_fma_f32 v12, -v8, v11, v10
	v_fmac_f32_e32 v11, v12, v9
	v_fma_f32 v8, -v8, v11, v10
	v_div_fmas_f32 v8, v8, v9, v11
	v_div_fixup_f32 v26, v8, v22, v18
	v_div_scale_f32 v8, s[0:1], v23, v23, v19
	v_rcp_f32_e32 v9, v8
	s_nop 0
	v_fma_f32 v10, -v8, v9, 1.0
	v_fmac_f32_e32 v9, v10, v9
	v_div_scale_f32 v10, vcc, v19, v23, v19
	v_mul_f32_e32 v11, v10, v9
	v_fma_f32 v12, -v8, v11, v10
	v_fmac_f32_e32 v11, v12, v9
	v_fma_f32 v8, -v8, v11, v10
	v_div_fmas_f32 v8, v8, v9, v11
	v_div_fixup_f32 v27, v8, v23, v19
	v_mul_f32_e32 v24, v24, v36
	v_mul_f32_e32 v25, v25, v37
	v_mul_f32_e32 v26, v26, v38
	v_mul_f32_e32 v27, v27, v39
	v_mul_f32_e32 v24, v24, v6
	v_mul_f32_e32 v25, v25, v6
	v_mul_f32_e32 v26, v26, v6
	v_mul_f32_e32 v27, v27, v6
	v_cvt_pk_bf16_f32 v30, v24, v25
	v_cvt_pk_bf16_f32 v31, v26, v27
	s_nop 1
	v_permlane32_swap_b32 v28, v30
	v_permlane32_swap_b32 v29, v31
	global_store_dwordx4 v2, v[28:31], s[88:89]
	s_waitcnt vmcnt(3)
	v_permlane32_swap_b32 v68, v70
	v_permlane32_swap_b32 v69, v71
	s_nop 0
	v_lshlrev_b32_e32 v16, 16, v68
	v_and_b32_e32 v17, 0xffff0000, v68
	v_lshlrev_b32_e32 v18, 16, v69
	v_and_b32_e32 v19, 0xffff0000, v69
	v_mul_f32_e32 v20, 0xbfb8aa3b, v16
	v_mul_f32_e32 v21, 0xbfb8aa3b, v17
	v_mul_f32_e32 v22, 0xbfb8aa3b, v18
	v_mul_f32_e32 v23, 0xbfb8aa3b, v19
	v_exp_f32_e32 v20, v20
	v_exp_f32_e32 v21, v21
	v_exp_f32_e32 v22, v22
	v_exp_f32_e32 v23, v23
	s_nop 0
	v_add_f32_e32 v20, 1.0, v20
	v_add_f32_e32 v21, 1.0, v21
	v_add_f32_e32 v22, 1.0, v22
	v_add_f32_e32 v23, 1.0, v23
	v_div_scale_f32 v8, s[0:1], v20, v20, v16
	v_rcp_f32_e32 v9, v8
	s_nop 0
	v_fma_f32 v10, -v8, v9, 1.0
	v_fmac_f32_e32 v9, v10, v9
	v_div_scale_f32 v10, vcc, v16, v20, v16
	v_mul_f32_e32 v11, v10, v9
	v_fma_f32 v12, -v8, v11, v10
	v_fmac_f32_e32 v11, v12, v9
	v_fma_f32 v8, -v8, v11, v10
	v_div_fmas_f32 v8, v8, v9, v11
	v_div_fixup_f32 v24, v8, v20, v16
	v_div_scale_f32 v8, s[0:1], v21, v21, v17
	v_rcp_f32_e32 v9, v8
	s_nop 0
	v_fma_f32 v10, -v8, v9, 1.0
	v_fmac_f32_e32 v9, v10, v9
	v_div_scale_f32 v10, vcc, v17, v21, v17
	v_mul_f32_e32 v11, v10, v9
	v_fma_f32 v12, -v8, v11, v10
	v_fmac_f32_e32 v11, v12, v9
	v_fma_f32 v8, -v8, v11, v10
	v_div_fmas_f32 v8, v8, v9, v11
	v_div_fixup_f32 v25, v8, v21, v17
	v_div_scale_f32 v8, s[0:1], v22, v22, v18
	v_rcp_f32_e32 v9, v8
	s_nop 0
	v_fma_f32 v10, -v8, v9, 1.0
	v_fmac_f32_e32 v9, v10, v9
	v_div_scale_f32 v10, vcc, v18, v22, v18
	v_mul_f32_e32 v11, v10, v9
	v_fma_f32 v12, -v8, v11, v10
	v_fmac_f32_e32 v11, v12, v9
	v_fma_f32 v8, -v8, v11, v10
	v_div_fmas_f32 v8, v8, v9, v11
	v_div_fixup_f32 v26, v8, v22, v18
	v_div_scale_f32 v8, s[0:1], v23, v23, v19
	v_rcp_f32_e32 v9, v8
	s_nop 0
	v_fma_f32 v10, -v8, v9, 1.0
	v_fmac_f32_e32 v9, v10, v9
	v_div_scale_f32 v10, vcc, v19, v23, v19
	v_mul_f32_e32 v11, v10, v9
	v_fma_f32 v12, -v8, v11, v10
	v_fmac_f32_e32 v11, v12, v9
	v_fma_f32 v8, -v8, v11, v10
	v_div_fmas_f32 v8, v8, v9, v11
	v_div_fixup_f32 v27, v8, v23, v19
	v_mul_f32_e32 v24, v24, v40
	v_mul_f32_e32 v25, v25, v41
	v_mul_f32_e32 v26, v26, v42
	v_mul_f32_e32 v27, v27, v43
	v_mul_f32_e32 v24, v24, v6
	v_mul_f32_e32 v25, v25, v6
	v_mul_f32_e32 v26, v26, v6
	v_mul_f32_e32 v27, v27, v6
	v_cvt_pk_bf16_f32 v28, v24, v25
	v_cvt_pk_bf16_f32 v29, v26, v27
	v_lshlrev_b32_e32 v16, 16, v70
	v_and_b32_e32 v17, 0xffff0000, v70
	v_lshlrev_b32_e32 v18, 16, v71
	v_and_b32_e32 v19, 0xffff0000, v71
	v_mul_f32_e32 v20, 0xbfb8aa3b, v16
	v_mul_f32_e32 v21, 0xbfb8aa3b, v17
	v_mul_f32_e32 v22, 0xbfb8aa3b, v18
	v_mul_f32_e32 v23, 0xbfb8aa3b, v19
	v_exp_f32_e32 v20, v20
	v_exp_f32_e32 v21, v21
	v_exp_f32_e32 v22, v22
	v_exp_f32_e32 v23, v23
	s_nop 0
	v_add_f32_e32 v20, 1.0, v20
	v_add_f32_e32 v21, 1.0, v21
	v_add_f32_e32 v22, 1.0, v22
	v_add_f32_e32 v23, 1.0, v23
	v_div_scale_f32 v8, s[0:1], v20, v20, v16
	v_rcp_f32_e32 v9, v8
	s_nop 0
	v_fma_f32 v10, -v8, v9, 1.0
	v_fmac_f32_e32 v9, v10, v9
	v_div_scale_f32 v10, vcc, v16, v20, v16
	v_mul_f32_e32 v11, v10, v9
	v_fma_f32 v12, -v8, v11, v10
	v_fmac_f32_e32 v11, v12, v9
	v_fma_f32 v8, -v8, v11, v10
	v_div_fmas_f32 v8, v8, v9, v11
	v_div_fixup_f32 v24, v8, v20, v16
	v_div_scale_f32 v8, s[0:1], v21, v21, v17
	v_rcp_f32_e32 v9, v8
	s_nop 0
	v_fma_f32 v10, -v8, v9, 1.0
	v_fmac_f32_e32 v9, v10, v9
	v_div_scale_f32 v10, vcc, v17, v21, v17
	v_mul_f32_e32 v11, v10, v9
	v_fma_f32 v12, -v8, v11, v10
	v_fmac_f32_e32 v11, v12, v9
	v_fma_f32 v8, -v8, v11, v10
	v_div_fmas_f32 v8, v8, v9, v11
	v_div_fixup_f32 v25, v8, v21, v17
	v_div_scale_f32 v8, s[0:1], v22, v22, v18
	v_rcp_f32_e32 v9, v8
	s_nop 0
	v_fma_f32 v10, -v8, v9, 1.0
	v_fmac_f32_e32 v9, v10, v9
	v_div_scale_f32 v10, vcc, v18, v22, v18
	v_mul_f32_e32 v11, v10, v9
	v_fma_f32 v12, -v8, v11, v10
	v_fmac_f32_e32 v11, v12, v9
	v_fma_f32 v8, -v8, v11, v10
	v_div_fmas_f32 v8, v8, v9, v11
	v_div_fixup_f32 v26, v8, v22, v18
	v_div_scale_f32 v8, s[0:1], v23, v23, v19
	v_rcp_f32_e32 v9, v8
	s_nop 0
	v_fma_f32 v10, -v8, v9, 1.0
	v_fmac_f32_e32 v9, v10, v9
	v_div_scale_f32 v10, vcc, v19, v23, v19
	v_mul_f32_e32 v11, v10, v9
	v_fma_f32 v12, -v8, v11, v10
	v_fmac_f32_e32 v11, v12, v9
	v_fma_f32 v8, -v8, v11, v10
	v_div_fmas_f32 v8, v8, v9, v11
	v_div_fixup_f32 v27, v8, v23, v19
	v_mul_f32_e32 v24, v24, v44
	v_mul_f32_e32 v25, v25, v45
	v_mul_f32_e32 v26, v26, v46
	v_mul_f32_e32 v27, v27, v47
	v_mul_f32_e32 v24, v24, v6
	v_mul_f32_e32 v25, v25, v6
	v_mul_f32_e32 v26, v26, v6
	v_mul_f32_e32 v27, v27, v6
	v_cvt_pk_bf16_f32 v30, v24, v25
	v_cvt_pk_bf16_f32 v31, v26, v27
	s_nop 1
	v_permlane32_swap_b32 v28, v30
	v_permlane32_swap_b32 v29, v31
	global_store_dwordx4 v2, v[28:31], s[88:89] offset:32
	s_waitcnt vmcnt(3)
	v_permlane32_swap_b32 v72, v74
	v_permlane32_swap_b32 v73, v75
	s_nop 0
	v_lshlrev_b32_e32 v16, 16, v72
	v_and_b32_e32 v17, 0xffff0000, v72
	v_lshlrev_b32_e32 v18, 16, v73
	v_and_b32_e32 v19, 0xffff0000, v73
	v_mul_f32_e32 v20, 0xbfb8aa3b, v16
	v_mul_f32_e32 v21, 0xbfb8aa3b, v17
	v_mul_f32_e32 v22, 0xbfb8aa3b, v18
	v_mul_f32_e32 v23, 0xbfb8aa3b, v19
	v_exp_f32_e32 v20, v20
	v_exp_f32_e32 v21, v21
	v_exp_f32_e32 v22, v22
	v_exp_f32_e32 v23, v23
	s_nop 0
	v_add_f32_e32 v20, 1.0, v20
	v_add_f32_e32 v21, 1.0, v21
	v_add_f32_e32 v22, 1.0, v22
	v_add_f32_e32 v23, 1.0, v23
	v_div_scale_f32 v8, s[0:1], v20, v20, v16
	v_rcp_f32_e32 v9, v8
	s_nop 0
	v_fma_f32 v10, -v8, v9, 1.0
	v_fmac_f32_e32 v9, v10, v9
	v_div_scale_f32 v10, vcc, v16, v20, v16
	v_mul_f32_e32 v11, v10, v9
	v_fma_f32 v12, -v8, v11, v10
	v_fmac_f32_e32 v11, v12, v9
	v_fma_f32 v8, -v8, v11, v10
	v_div_fmas_f32 v8, v8, v9, v11
	v_div_fixup_f32 v24, v8, v20, v16
	v_div_scale_f32 v8, s[0:1], v21, v21, v17
	v_rcp_f32_e32 v9, v8
	s_nop 0
	v_fma_f32 v10, -v8, v9, 1.0
	v_fmac_f32_e32 v9, v10, v9
	v_div_scale_f32 v10, vcc, v17, v21, v17
	v_mul_f32_e32 v11, v10, v9
	v_fma_f32 v12, -v8, v11, v10
	v_fmac_f32_e32 v11, v12, v9
	v_fma_f32 v8, -v8, v11, v10
	v_div_fmas_f32 v8, v8, v9, v11
	v_div_fixup_f32 v25, v8, v21, v17
	v_div_scale_f32 v8, s[0:1], v22, v22, v18
	v_rcp_f32_e32 v9, v8
	s_nop 0
	v_fma_f32 v10, -v8, v9, 1.0
	v_fmac_f32_e32 v9, v10, v9
	v_div_scale_f32 v10, vcc, v18, v22, v18
	v_mul_f32_e32 v11, v10, v9
	v_fma_f32 v12, -v8, v11, v10
	v_fmac_f32_e32 v11, v12, v9
	v_fma_f32 v8, -v8, v11, v10
	v_div_fmas_f32 v8, v8, v9, v11
	v_div_fixup_f32 v26, v8, v22, v18
	v_div_scale_f32 v8, s[0:1], v23, v23, v19
	v_rcp_f32_e32 v9, v8
	s_nop 0
	v_fma_f32 v10, -v8, v9, 1.0
	v_fmac_f32_e32 v9, v10, v9
	v_div_scale_f32 v10, vcc, v19, v23, v19
	v_mul_f32_e32 v11, v10, v9
	v_fma_f32 v12, -v8, v11, v10
	v_fmac_f32_e32 v11, v12, v9
	v_fma_f32 v8, -v8, v11, v10
	v_div_fmas_f32 v8, v8, v9, v11
	v_div_fixup_f32 v27, v8, v23, v19
	v_mul_f32_e32 v24, v24, v48
	v_mul_f32_e32 v25, v25, v49
	v_mul_f32_e32 v26, v26, v50
	v_mul_f32_e32 v27, v27, v51
	v_mul_f32_e32 v24, v24, v6
	v_mul_f32_e32 v25, v25, v6
	v_mul_f32_e32 v26, v26, v6
	v_mul_f32_e32 v27, v27, v6
	v_cvt_pk_bf16_f32 v28, v24, v25
	v_cvt_pk_bf16_f32 v29, v26, v27
	v_lshlrev_b32_e32 v16, 16, v74
	v_and_b32_e32 v17, 0xffff0000, v74
	v_lshlrev_b32_e32 v18, 16, v75
	v_and_b32_e32 v19, 0xffff0000, v75
	v_mul_f32_e32 v20, 0xbfb8aa3b, v16
	v_mul_f32_e32 v21, 0xbfb8aa3b, v17
	v_mul_f32_e32 v22, 0xbfb8aa3b, v18
	v_mul_f32_e32 v23, 0xbfb8aa3b, v19
	v_exp_f32_e32 v20, v20
	v_exp_f32_e32 v21, v21
	v_exp_f32_e32 v22, v22
	v_exp_f32_e32 v23, v23
	s_nop 0
	v_add_f32_e32 v20, 1.0, v20
	v_add_f32_e32 v21, 1.0, v21
	v_add_f32_e32 v22, 1.0, v22
	v_add_f32_e32 v23, 1.0, v23
	v_div_scale_f32 v8, s[0:1], v20, v20, v16
	v_rcp_f32_e32 v9, v8
	s_nop 0
	v_fma_f32 v10, -v8, v9, 1.0
	v_fmac_f32_e32 v9, v10, v9
	v_div_scale_f32 v10, vcc, v16, v20, v16
	v_mul_f32_e32 v11, v10, v9
	v_fma_f32 v12, -v8, v11, v10
	v_fmac_f32_e32 v11, v12, v9
	v_fma_f32 v8, -v8, v11, v10
	v_div_fmas_f32 v8, v8, v9, v11
	v_div_fixup_f32 v24, v8, v20, v16
	v_div_scale_f32 v8, s[0:1], v21, v21, v17
	v_rcp_f32_e32 v9, v8
	s_nop 0
	v_fma_f32 v10, -v8, v9, 1.0
	v_fmac_f32_e32 v9, v10, v9
	v_div_scale_f32 v10, vcc, v17, v21, v17
	v_mul_f32_e32 v11, v10, v9
	v_fma_f32 v12, -v8, v11, v10
	v_fmac_f32_e32 v11, v12, v9
	v_fma_f32 v8, -v8, v11, v10
	v_div_fmas_f32 v8, v8, v9, v11
	v_div_fixup_f32 v25, v8, v21, v17
	v_div_scale_f32 v8, s[0:1], v22, v22, v18
	v_rcp_f32_e32 v9, v8
	s_nop 0
	v_fma_f32 v10, -v8, v9, 1.0
	v_fmac_f32_e32 v9, v10, v9
	v_div_scale_f32 v10, vcc, v18, v22, v18
	v_mul_f32_e32 v11, v10, v9
	v_fma_f32 v12, -v8, v11, v10
	v_fmac_f32_e32 v11, v12, v9
	v_fma_f32 v8, -v8, v11, v10
	v_div_fmas_f32 v8, v8, v9, v11
	v_div_fixup_f32 v26, v8, v22, v18
	v_div_scale_f32 v8, s[0:1], v23, v23, v19
	v_rcp_f32_e32 v9, v8
	s_nop 0
	v_fma_f32 v10, -v8, v9, 1.0
	v_fmac_f32_e32 v9, v10, v9
	v_div_scale_f32 v10, vcc, v19, v23, v19
	v_mul_f32_e32 v11, v10, v9
	v_fma_f32 v12, -v8, v11, v10
	v_fmac_f32_e32 v11, v12, v9
	v_fma_f32 v8, -v8, v11, v10
	v_div_fmas_f32 v8, v8, v9, v11
	v_div_fixup_f32 v27, v8, v23, v19
	v_mul_f32_e32 v24, v24, v52
	v_mul_f32_e32 v25, v25, v53
	v_mul_f32_e32 v26, v26, v54
	v_mul_f32_e32 v27, v27, v55
	v_mul_f32_e32 v24, v24, v6
	v_mul_f32_e32 v25, v25, v6
	v_mul_f32_e32 v26, v26, v6
	v_mul_f32_e32 v27, v27, v6
	v_cvt_pk_bf16_f32 v30, v24, v25
	v_cvt_pk_bf16_f32 v31, v26, v27
	s_nop 1
	v_permlane32_swap_b32 v28, v30
	v_permlane32_swap_b32 v29, v31
	global_store_dwordx4 v2, v[28:31], s[88:89] offset:64
	s_waitcnt vmcnt(3)
	v_permlane32_swap_b32 v76, v78
	v_permlane32_swap_b32 v77, v79
	s_nop 0
	v_lshlrev_b32_e32 v16, 16, v76
	v_and_b32_e32 v17, 0xffff0000, v76
	v_lshlrev_b32_e32 v18, 16, v77
	v_and_b32_e32 v19, 0xffff0000, v77
	v_mul_f32_e32 v20, 0xbfb8aa3b, v16
	v_mul_f32_e32 v21, 0xbfb8aa3b, v17
	v_mul_f32_e32 v22, 0xbfb8aa3b, v18
	v_mul_f32_e32 v23, 0xbfb8aa3b, v19
	v_exp_f32_e32 v20, v20
	v_exp_f32_e32 v21, v21
	v_exp_f32_e32 v22, v22
	v_exp_f32_e32 v23, v23
	s_nop 0
	v_add_f32_e32 v20, 1.0, v20
	v_add_f32_e32 v21, 1.0, v21
	v_add_f32_e32 v22, 1.0, v22
	v_add_f32_e32 v23, 1.0, v23
	v_div_scale_f32 v8, s[0:1], v20, v20, v16
	v_rcp_f32_e32 v9, v8
	s_nop 0
	v_fma_f32 v10, -v8, v9, 1.0
	v_fmac_f32_e32 v9, v10, v9
	v_div_scale_f32 v10, vcc, v16, v20, v16
	v_mul_f32_e32 v11, v10, v9
	v_fma_f32 v12, -v8, v11, v10
	v_fmac_f32_e32 v11, v12, v9
	v_fma_f32 v8, -v8, v11, v10
	v_div_fmas_f32 v8, v8, v9, v11
	v_div_fixup_f32 v24, v8, v20, v16
	v_div_scale_f32 v8, s[0:1], v21, v21, v17
	v_rcp_f32_e32 v9, v8
	s_nop 0
	v_fma_f32 v10, -v8, v9, 1.0
	v_fmac_f32_e32 v9, v10, v9
	v_div_scale_f32 v10, vcc, v17, v21, v17
	v_mul_f32_e32 v11, v10, v9
	v_fma_f32 v12, -v8, v11, v10
	v_fmac_f32_e32 v11, v12, v9
	v_fma_f32 v8, -v8, v11, v10
	v_div_fmas_f32 v8, v8, v9, v11
	v_div_fixup_f32 v25, v8, v21, v17
	v_div_scale_f32 v8, s[0:1], v22, v22, v18
	v_rcp_f32_e32 v9, v8
	s_nop 0
	v_fma_f32 v10, -v8, v9, 1.0
	v_fmac_f32_e32 v9, v10, v9
	v_div_scale_f32 v10, vcc, v18, v22, v18
	v_mul_f32_e32 v11, v10, v9
	v_fma_f32 v12, -v8, v11, v10
	v_fmac_f32_e32 v11, v12, v9
	v_fma_f32 v8, -v8, v11, v10
	v_div_fmas_f32 v8, v8, v9, v11
	v_div_fixup_f32 v26, v8, v22, v18
	v_div_scale_f32 v8, s[0:1], v23, v23, v19
	v_rcp_f32_e32 v9, v8
	s_nop 0
	v_fma_f32 v10, -v8, v9, 1.0
	v_fmac_f32_e32 v9, v10, v9
	v_div_scale_f32 v10, vcc, v19, v23, v19
	v_mul_f32_e32 v11, v10, v9
	v_fma_f32 v12, -v8, v11, v10
	v_fmac_f32_e32 v11, v12, v9
	v_fma_f32 v8, -v8, v11, v10
	v_div_fmas_f32 v8, v8, v9, v11
	v_div_fixup_f32 v27, v8, v23, v19
	v_mul_f32_e32 v24, v24, v56
	v_mul_f32_e32 v25, v25, v57
	v_mul_f32_e32 v26, v26, v58
	v_mul_f32_e32 v27, v27, v59
	v_mul_f32_e32 v24, v24, v6
	v_mul_f32_e32 v25, v25, v6
	v_mul_f32_e32 v26, v26, v6
	v_mul_f32_e32 v27, v27, v6
	v_cvt_pk_bf16_f32 v28, v24, v25
	v_cvt_pk_bf16_f32 v29, v26, v27
	v_lshlrev_b32_e32 v16, 16, v78
	v_and_b32_e32 v17, 0xffff0000, v78
	v_lshlrev_b32_e32 v18, 16, v79
	v_and_b32_e32 v19, 0xffff0000, v79
	v_mul_f32_e32 v20, 0xbfb8aa3b, v16
	v_mul_f32_e32 v21, 0xbfb8aa3b, v17
	v_mul_f32_e32 v22, 0xbfb8aa3b, v18
	v_mul_f32_e32 v23, 0xbfb8aa3b, v19
	v_exp_f32_e32 v20, v20
	v_exp_f32_e32 v21, v21
	v_exp_f32_e32 v22, v22
	v_exp_f32_e32 v23, v23
	s_nop 0
	v_add_f32_e32 v20, 1.0, v20
	v_add_f32_e32 v21, 1.0, v21
	v_add_f32_e32 v22, 1.0, v22
	v_add_f32_e32 v23, 1.0, v23
	v_div_scale_f32 v8, s[0:1], v20, v20, v16
	v_rcp_f32_e32 v9, v8
	s_nop 0
	v_fma_f32 v10, -v8, v9, 1.0
	v_fmac_f32_e32 v9, v10, v9
	v_div_scale_f32 v10, vcc, v16, v20, v16
	v_mul_f32_e32 v11, v10, v9
	v_fma_f32 v12, -v8, v11, v10
	v_fmac_f32_e32 v11, v12, v9
	v_fma_f32 v8, -v8, v11, v10
	v_div_fmas_f32 v8, v8, v9, v11
	v_div_fixup_f32 v24, v8, v20, v16
	v_div_scale_f32 v8, s[0:1], v21, v21, v17
	v_rcp_f32_e32 v9, v8
	s_nop 0
	v_fma_f32 v10, -v8, v9, 1.0
	v_fmac_f32_e32 v9, v10, v9
	v_div_scale_f32 v10, vcc, v17, v21, v17
	v_mul_f32_e32 v11, v10, v9
	v_fma_f32 v12, -v8, v11, v10
	v_fmac_f32_e32 v11, v12, v9
	v_fma_f32 v8, -v8, v11, v10
	v_div_fmas_f32 v8, v8, v9, v11
	v_div_fixup_f32 v25, v8, v21, v17
	v_div_scale_f32 v8, s[0:1], v22, v22, v18
	v_rcp_f32_e32 v9, v8
	s_nop 0
	v_fma_f32 v10, -v8, v9, 1.0
	v_fmac_f32_e32 v9, v10, v9
	v_div_scale_f32 v10, vcc, v18, v22, v18
	v_mul_f32_e32 v11, v10, v9
	v_fma_f32 v12, -v8, v11, v10
	v_fmac_f32_e32 v11, v12, v9
	v_fma_f32 v8, -v8, v11, v10
	v_div_fmas_f32 v8, v8, v9, v11
	v_div_fixup_f32 v26, v8, v22, v18
	v_div_scale_f32 v8, s[0:1], v23, v23, v19
	v_rcp_f32_e32 v9, v8
	s_nop 0
	v_fma_f32 v10, -v8, v9, 1.0
	v_fmac_f32_e32 v9, v10, v9
	v_div_scale_f32 v10, vcc, v19, v23, v19
	v_mul_f32_e32 v11, v10, v9
	v_fma_f32 v12, -v8, v11, v10
	v_fmac_f32_e32 v11, v12, v9
	v_fma_f32 v8, -v8, v11, v10
	v_div_fmas_f32 v8, v8, v9, v11
	v_div_fixup_f32 v27, v8, v23, v19
	v_mul_f32_e32 v24, v24, v60
	v_mul_f32_e32 v25, v25, v61
	v_mul_f32_e32 v26, v26, v62
	v_mul_f32_e32 v27, v27, v63
	v_mul_f32_e32 v24, v24, v6
	v_mul_f32_e32 v25, v25, v6
	v_mul_f32_e32 v26, v26, v6
	v_mul_f32_e32 v27, v27, v6
	v_cvt_pk_bf16_f32 v30, v24, v25
	v_cvt_pk_bf16_f32 v31, v26, v27
	s_nop 1
	v_permlane32_swap_b32 v28, v30
	v_permlane32_swap_b32 v29, v31
	global_store_dwordx4 v2, v[28:31], s[88:89] offset:96
	s_add_i32 s2, s2, s71
	v_readlane_b32 s0, v206, 49
	s_nop 0
	s_cmp_ge_u32 s2, s0
	s_cbranch_scc0 .LBB0_350
	s_branch .LBB0_343
.Ltramp176:
	s_branch .LBB0_176
.Lat_stab0:
	v_sub_f32_e32 v0, v0, v129
	v_sub_f32_e32 v1, v1, v129
	v_sub_f32_e32 v2, v2, v129
	v_sub_f32_e32 v3, v3, v129
	v_sub_f32_e32 v4, v4, v129
	v_sub_f32_e32 v5, v5, v129
	v_sub_f32_e32 v6, v6, v129
	v_sub_f32_e32 v7, v7, v129
	v_sub_f32_e32 v8, v8, v129
	v_sub_f32_e32 v9, v9, v129
	v_sub_f32_e32 v10, v10, v129
	v_sub_f32_e32 v11, v11, v129
	v_sub_f32_e32 v12, v12, v129
	v_sub_f32_e32 v13, v13, v129
	v_sub_f32_e32 v14, v14, v129
	v_sub_f32_e32 v15, v15, v129
	s_branch .Lat_stab0_ret
